# phase3_scan_stores_plain_instead_of_write_through
# speedup vs baseline: 1.0050x; 1.0050x over previous
.LBB0_577:
	v_lshlrev_b32_e32 v50, 16, v25
	v_and_b32_e32 v51, 0xffff0000, v25
	s_waitcnt vmcnt(13)
	v_pk_fma_f32 v[40:41], v[20:21], v[40:41], v[50:51] op_sel_hi:[0,1,1]
	v_and_b32_sdwa v25, v40, v9 dst_sel:DWORD dst_unused:UNUSED_PAD src0_sel:WORD_1 src1_sel:DWORD
	v_and_b32_sdwa v20, v41, v9 dst_sel:DWORD dst_unused:UNUSED_PAD src0_sel:WORD_1 src1_sel:DWORD
	v_add3_u32 v25, v40, v25, s0
	v_lshl_add_u64 v[50:51], v[26:27], 0, s[38:39]
	v_add3_u32 v20, v41, v20, s0
	v_lshrrev_b32_e32 v25, 16, v25
	v_and_or_b32 v20, v20, s77, v25
	global_store_dword v[50:51], v20, off
	s_nop 1
	v_lshlrev_b32_e32 v50, 16, v47
	v_and_b32_e32 v51, 0xffff0000, v47
	s_waitcnt vmcnt(7)
	v_pk_fma_f32 v[40:41], v[38:39], v[40:41], v[50:51] op_sel_hi:[0,1,1]
	v_and_b32_sdwa v25, v40, v9 dst_sel:DWORD dst_unused:UNUSED_PAD src0_sel:WORD_1 src1_sel:DWORD
	v_and_b32_sdwa v20, v41, v9 dst_sel:DWORD dst_unused:UNUSED_PAD src0_sel:WORD_1 src1_sel:DWORD
	v_add3_u32 v25, v40, v25, s0
	v_lshlrev_b32_e32 v50, 16, v46
	v_and_b32_e32 v51, 0xffff0000, v46
	v_add3_u32 v20, v41, v20, s0
	v_lshrrev_b32_e32 v25, 16, v25
	s_waitcnt vmcnt(6)
	v_pk_fma_f32 v[40:41], v[36:37], v[40:41], v[50:51] op_sel_hi:[0,1,1]
	v_and_or_b32 v20, v20, s77, v25
	v_and_b32_sdwa v25, v40, v9 dst_sel:DWORD dst_unused:UNUSED_PAD src0_sel:WORD_1 src1_sel:DWORD
	v_lshl_add_u64 v[52:53], v[26:27], 0, s[40:41]
	global_store_dword v[52:53], v20, off
	s_nop 1
	v_and_b32_sdwa v20, v41, v9 dst_sel:DWORD dst_unused:UNUSED_PAD src0_sel:WORD_1 src1_sel:DWORD
	v_add3_u32 v25, v40, v25, s0
	v_lshl_add_u64 v[46:47], v[26:27], 0, s[42:43]
	v_add3_u32 v20, v41, v20, s0
	v_lshrrev_b32_e32 v25, 16, v25
	v_and_or_b32 v20, v20, s77, v25
	global_store_dword v[46:47], v20, off
	s_nop 1
	v_lshlrev_b32_e32 v46, 16, v45
	v_and_b32_e32 v47, 0xffff0000, v45
	s_waitcnt vmcnt(5)
	v_pk_fma_f32 v[40:41], v[34:35], v[40:41], v[46:47] op_sel_hi:[0,1,1]
	v_and_b32_sdwa v25, v40, v9 dst_sel:DWORD dst_unused:UNUSED_PAD src0_sel:WORD_1 src1_sel:DWORD
	v_and_b32_sdwa v20, v41, v9 dst_sel:DWORD dst_unused:UNUSED_PAD src0_sel:WORD_1 src1_sel:DWORD
	v_add3_u32 v25, v40, v25, s0
	v_lshlrev_b32_e32 v46, 16, v44
	v_and_b32_e32 v47, 0xffff0000, v44
	v_add3_u32 v20, v41, v20, s0
	v_lshrrev_b32_e32 v25, 16, v25
	s_waitcnt vmcnt(4)
	v_pk_fma_f32 v[40:41], v[32:33], v[40:41], v[46:47] op_sel_hi:[0,1,1]
	v_and_or_b32 v20, v20, s77, v25
	v_and_b32_sdwa v25, v40, v9 dst_sel:DWORD dst_unused:UNUSED_PAD src0_sel:WORD_1 src1_sel:DWORD
	v_lshl_add_u64 v[50:51], v[26:27], 0, s[44:45]
	global_store_dword v[50:51], v20, off
	s_nop 1
	v_and_b32_sdwa v20, v41, v9 dst_sel:DWORD dst_unused:UNUSED_PAD src0_sel:WORD_1 src1_sel:DWORD
	v_add3_u32 v25, v40, v25, s0
	v_lshl_add_u64 v[44:45], v[26:27], 0, s[46:47]
	v_add3_u32 v20, v41, v20, s0
	v_lshrrev_b32_e32 v25, 16, v25
	v_and_or_b32 v20, v20, s77, v25
	global_store_dword v[44:45], v20, off
	s_nop 1
	v_lshlrev_b32_e32 v44, 16, v43
	v_and_b32_e32 v45, 0xffff0000, v43
	s_waitcnt vmcnt(3)
	v_pk_fma_f32 v[40:41], v[30:31], v[40:41], v[44:45] op_sel_hi:[0,1,1]
	v_and_b32_sdwa v25, v40, v9 dst_sel:DWORD dst_unused:UNUSED_PAD src0_sel:WORD_1 src1_sel:DWORD
	v_and_b32_sdwa v20, v41, v9 dst_sel:DWORD dst_unused:UNUSED_PAD src0_sel:WORD_1 src1_sel:DWORD
	v_add3_u32 v25, v40, v25, s0
	v_lshlrev_b32_e32 v44, 16, v42
	v_and_b32_e32 v45, 0xffff0000, v42
	v_add3_u32 v20, v41, v20, s0
	v_lshrrev_b32_e32 v25, 16, v25
	s_waitcnt vmcnt(2)
	v_pk_fma_f32 v[40:41], v[28:29], v[40:41], v[44:45] op_sel_hi:[0,1,1]
	v_and_or_b32 v20, v20, s77, v25
	v_and_b32_sdwa v25, v40, v9 dst_sel:DWORD dst_unused:UNUSED_PAD src0_sel:WORD_1 src1_sel:DWORD
	v_lshl_add_u64 v[46:47], v[26:27], 0, s[48:49]
	global_store_dword v[46:47], v20, off
	s_nop 1
	v_and_b32_sdwa v20, v41, v9 dst_sel:DWORD dst_unused:UNUSED_PAD src0_sel:WORD_1 src1_sel:DWORD
	v_add3_u32 v25, v40, v25, s0
	v_add3_u32 v20, v41, v20, s0
	v_lshrrev_b32_e32 v25, 16, v25
	v_lshlrev_b32_e32 v38, 16, v39
	v_and_b32_e32 v39, 0xffff0000, v39
	v_and_or_b32 v20, v20, s77, v25
	s_waitcnt vmcnt(1)
	v_pk_fma_f32 v[24:25], v[24:25], v[40:41], v[38:39] op_sel_hi:[0,1,1]
	v_and_b32_sdwa v28, v24, v9 dst_sel:DWORD dst_unused:UNUSED_PAD src0_sel:WORD_1 src1_sel:DWORD
	v_lshl_add_u64 v[42:43], v[26:27], 0, s[50:51]
	global_store_dword v[42:43], v20, off
	s_nop 1
	v_and_b32_sdwa v20, v25, v9 dst_sel:DWORD dst_unused:UNUSED_PAD src0_sel:WORD_1 src1_sel:DWORD
	v_add3_u32 v28, v24, v28, s0
	v_lshl_add_u64 v[26:27], v[26:27], 0, s[52:53]
	v_add3_u32 v20, v25, v20, s0
	v_lshrrev_b32_e32 v28, 16, v28
	v_and_or_b32 v20, v20, s77, v28
	global_store_dword v[26:27], v20, off
	s_nop 1
	v_lshlrev_b32_e32 v26, 16, v23
	v_and_b32_e32 v27, 0xffff0000, v23
	s_waitcnt vmcnt(0)
	v_pk_fma_f32 v[40:41], v[22:23], v[24:25], v[26:27] op_sel_hi:[0,1,1]
	s_add_i32 s85, s85, 16
	v_lshl_add_u64 v[2:3], v[2:3], 0, s[54:55]
	v_lshl_add_u64 v[4:5], v[4:5], 0, s[56:57]
	s_andn2_b64 vcc, exec, s[82:83]
	v_mov_b32_e32 v20, v48
	v_mov_b32_e32 v25, v37
	s_cbranch_vccz .LBB0_580
.LBB0_578:
	s_mov_b32 s82, 0xffe20000
	v_add_co_u32_e32 v22, vcc, s82, v4
	s_mov_b32 s82, 0xffe40000
	s_nop 0
	v_addc_co_u32_e32 v23, vcc, -1, v5, vcc
	v_add_co_u32_e32 v26, vcc, s82, v4
	s_mov_b32 s82, 0xffe60000
	s_nop 0
	v_addc_co_u32_e32 v27, vcc, -1, v5, vcc
	v_add_co_u32_e32 v38, vcc, s82, v4
	s_mov_b32 s82, 0xffe80000
	s_nop 0
	v_addc_co_u32_e32 v39, vcc, -1, v5, vcc
	v_add_co_u32_e32 v42, vcc, s82, v4
	s_mov_b32 s82, 0xffea0000
	s_nop 0
	v_addc_co_u32_e32 v43, vcc, -1, v5, vcc
	v_add_co_u32_e32 v48, vcc, s82, v4
	s_mov_b32 s82, 0xffec0000
	s_nop 0
	v_addc_co_u32_e32 v49, vcc, -1, v5, vcc
	v_add_co_u32_e32 v50, vcc, s82, v4
	s_mov_b32 s82, 0xffee0000
	s_nop 0
	v_addc_co_u32_e32 v51, vcc, -1, v5, vcc
	v_add_co_u32_e32 v52, vcc, s82, v4
	s_mov_b32 s82, 0xfff00000
	s_nop 0
	v_addc_co_u32_e32 v53, vcc, -1, v5, vcc
	v_add_co_u32_e32 v54, vcc, s82, v4
	s_mov_b32 s82, 0xffd20000
	s_nop 0
	v_addc_co_u32_e32 v55, vcc, -1, v5, vcc
	global_load_dword v47, v[22:23], off
	global_load_dword v46, v[26:27], off
	global_load_dword v45, v[38:39], off
	global_load_dword v44, v[42:43], off
	s_nop 0
	global_load_dword v43, v[48:49], off
	global_load_dword v42, v[50:51], off
	global_load_dword v39, v[52:53], off
	global_load_dword v23, v[54:55], off
	global_load_dword v38, v[2:3], off offset:-480
	global_load_dword v36, v[2:3], off offset:-448
	global_load_dword v34, v[2:3], off offset:-416
	global_load_dword v32, v[2:3], off offset:-384
	global_load_dword v30, v[2:3], off offset:-352
	global_load_dword v28, v[2:3], off offset:-320
	global_load_dword v24, v[2:3], off offset:-288
	global_load_dword v22, v[2:3], off offset:-256
	v_bfe_u32 v48, v40, 16, 1
	v_bfe_u32 v49, v41, 16, 1
	v_lshlrev_b32_e32 v50, 16, v1
	v_and_b32_e32 v51, 0xffff0000, v1
	v_add3_u32 v48, v40, v48, s0
	v_add3_u32 v49, v41, v49, s0
	v_pk_fma_f32 v[40:41], v[40:41], v[6:7], v[50:51] op_sel_hi:[1,0,1]
	s_mov_b32 s83, -1
	v_and_b32_sdwa v51, v40, v9 dst_sel:DWORD dst_unused:UNUSED_PAD src0_sel:WORD_1 src1_sel:DWORD
	v_and_b32_sdwa v50, v41, v9 dst_sel:DWORD dst_unused:UNUSED_PAD src0_sel:WORD_1 src1_sel:DWORD
	v_add3_u32 v51, v40, v51, s0
	v_lshrrev_b32_e32 v48, 16, v48
	v_add3_u32 v50, v41, v50, s0
	v_lshrrev_b32_e32 v51, 16, v51
	v_lshl_add_u64 v[26:27], v[4:5], 0, s[82:83]
	v_and_or_b32 v48, v49, s77, v48
	global_store_dword v[26:27], v48, off
	s_nop 1
	v_and_or_b32 v50, v50, s77, v51
	v_lshl_add_u64 v[48:49], v[4:5], 0, s[20:21]
	global_store_dword v[48:49], v50, off
	s_nop 1
	v_lshlrev_b32_e32 v50, 16, v7
	v_and_b32_e32 v51, 0xffff0000, v7
	v_pk_fma_f32 v[40:41], v[8:9], v[40:41], v[50:51] op_sel_hi:[0,1,1]
	v_and_b32_sdwa v51, v40, v9 dst_sel:DWORD dst_unused:UNUSED_PAD src0_sel:WORD_1 src1_sel:DWORD
	v_and_b32_sdwa v50, v41, v9 dst_sel:DWORD dst_unused:UNUSED_PAD src0_sel:WORD_1 src1_sel:DWORD
	v_add3_u32 v51, v40, v51, s0
	v_add3_u32 v50, v41, v50, s0
	v_lshrrev_b32_e32 v51, 16, v51
	v_and_or_b32 v50, v50, s77, v51
	v_lshl_add_u64 v[48:49], v[4:5], 0, s[22:23]
	global_store_dword v[48:49], v50, off
	s_nop 1
	v_lshlrev_b32_e32 v50, 16, v21
	v_and_b32_e32 v51, 0xffff0000, v21
	v_pk_fma_f32 v[40:41], v[10:11], v[40:41], v[50:51] op_sel_hi:[0,1,1]
	v_and_b32_sdwa v51, v40, v9 dst_sel:DWORD dst_unused:UNUSED_PAD src0_sel:WORD_1 src1_sel:DWORD
	v_and_b32_sdwa v50, v41, v9 dst_sel:DWORD dst_unused:UNUSED_PAD src0_sel:WORD_1 src1_sel:DWORD
	v_add3_u32 v51, v40, v51, s0
	v_add3_u32 v50, v41, v50, s0
	v_lshrrev_b32_e32 v51, 16, v51
	v_and_or_b32 v50, v50, s77, v51
	v_lshl_add_u64 v[48:49], v[4:5], 0, s[26:27]
	global_store_dword v[48:49], v50, off
	s_nop 1
	v_lshlrev_b32_e32 v50, 16, v29
	v_and_b32_e32 v51, 0xffff0000, v29
	v_pk_fma_f32 v[40:41], v[12:13], v[40:41], v[50:51] op_sel_hi:[0,1,1]
	v_and_b32_sdwa v51, v40, v9 dst_sel:DWORD dst_unused:UNUSED_PAD src0_sel:WORD_1 src1_sel:DWORD
	v_and_b32_sdwa v50, v41, v9 dst_sel:DWORD dst_unused:UNUSED_PAD src0_sel:WORD_1 src1_sel:DWORD
	v_add3_u32 v51, v40, v51, s0
	v_lshl_add_u64 v[48:49], v[4:5], 0, s[28:29]
	v_add3_u32 v50, v41, v50, s0
	v_lshrrev_b32_e32 v51, 16, v51
	v_and_or_b32 v50, v50, s77, v51
	global_store_dword v[48:49], v50, off
	s_nop 1
	v_lshlrev_b32_e32 v48, 16, v31
	v_and_b32_e32 v49, 0xffff0000, v31
	v_pk_fma_f32 v[40:41], v[14:15], v[40:41], v[48:49] op_sel_hi:[0,1,1]
	v_bfe_u32 v48, v40, 16, 1
	v_add3_u32 v48, v40, v48, s0
	v_bfe_u32 v49, v41, 16, 1
	v_lshrrev_b32_e32 v48, 16, v48
	v_add3_u32 v49, v41, v49, s0
	v_and_or_b32 v48, v49, s77, v48
	v_lshl_add_u64 v[50:51], v[4:5], 0, s[30:31]
	global_store_dword v[50:51], v48, off
	s_nop 1
	v_lshlrev_b32_e32 v48, 16, v33
	v_and_b32_e32 v49, 0xffff0000, v33
	v_pk_fma_f32 v[40:41], v[16:17], v[40:41], v[48:49] op_sel_hi:[0,1,1]
	v_bfe_u32 v48, v40, 16, 1
	v_add3_u32 v48, v40, v48, s0
	v_bfe_u32 v49, v41, 16, 1
	v_lshrrev_b32_e32 v48, 16, v48
	v_add3_u32 v49, v41, v49, s0
	v_and_or_b32 v48, v49, s77, v48
	v_lshl_add_u64 v[52:53], v[4:5], 0, s[34:35]
	global_store_dword v[52:53], v48, off
	s_nop 1
	v_lshlrev_b32_e32 v48, 16, v35
	v_and_b32_e32 v49, 0xffff0000, v35
	v_pk_fma_f32 v[40:41], v[18:19], v[40:41], v[48:49] op_sel_hi:[0,1,1]
	v_bfe_u32 v48, v40, 16, 1
	v_add3_u32 v48, v40, v48, s0
	v_bfe_u32 v49, v41, 16, 1
	v_lshrrev_b32_e32 v48, 16, v48
	v_add3_u32 v49, v41, v49, s0
	v_lshl_add_u64 v[54:55], v[4:5], 0, s[36:37]
	v_and_or_b32 v48, v49, s77, v48
	global_store_dword v[54:55], v48, off
	s_nop 1
	s_cmpk_gt_u32 s85, 0xef
	s_cselect_b64 s[82:83], -1, 0
	s_and_b64 vcc, exec, s[82:83]
	v_mov_b32_e32 v48, v20
	s_cbranch_vccnz .LBB0_577
	v_add_co_u32_e32 v6, vcc, 0xfff20000, v4
	s_nop 1
	v_addc_co_u32_e32 v7, vcc, -1, v5, vcc
	v_add_co_u32_e32 v48, vcc, 0xfff40000, v4
	s_nop 1
	v_addc_co_u32_e32 v49, vcc, -1, v5, vcc
	v_add_co_u32_e32 v50, vcc, 0xfff60000, v4
	s_nop 1
	v_addc_co_u32_e32 v51, vcc, -1, v5, vcc
	v_add_co_u32_e32 v52, vcc, 0xfff80000, v4
	s_nop 1
	v_addc_co_u32_e32 v53, vcc, -1, v5, vcc
	v_add_co_u32_e32 v54, vcc, 0xfffa0000, v4
	s_nop 1
	v_addc_co_u32_e32 v55, vcc, -1, v5, vcc
	v_add_co_u32_e32 v56, vcc, 0xfffc0000, v4
	s_nop 1
	v_addc_co_u32_e32 v57, vcc, -1, v5, vcc
	v_add_co_u32_e32 v58, vcc, 0xfffe0000, v4
	s_nop 1
	v_addc_co_u32_e32 v59, vcc, -1, v5, vcc
	global_load_dword v1, v[6:7], off
	s_nop 0
	global_load_dword v7, v[48:49], off
	global_load_dword v21, v[50:51], off
	global_load_dword v29, v[52:53], off
	global_load_dword v31, v[54:55], off
	global_load_dword v33, v[56:57], off
	global_load_dword v35, v[58:59], off
	global_load_dword v37, v[4:5], off
	global_load_dword v6, v[2:3], off offset:-224
	global_load_dword v8, v[2:3], off offset:-192
	global_load_dword v10, v[2:3], off offset:-160
	global_load_dword v12, v[2:3], off offset:-128
	global_load_dword v14, v[2:3], off offset:-96
	global_load_dword v16, v[2:3], off offset:-64
	global_load_dword v18, v[2:3], off offset:-32
	global_load_dword v48, v[2:3], off
	s_branch .LBB0_577

.LBB0_582:
	v_lshlrev_b32_e32 v46, 16, v20
	v_and_b32_e32 v47, 0xffff0000, v20
	v_pk_fma_f32 v[6:7], v[4:5], v[6:7], v[46:47]
	v_lshl_add_u64 v[30:31], v[2:3], 0, s[38:39]
	v_and_b32_sdwa v46, v6, v9 dst_sel:DWORD dst_unused:UNUSED_PAD src0_sel:WORD_1 src1_sel:DWORD
	v_and_b32_sdwa v20, v7, v9 dst_sel:DWORD dst_unused:UNUSED_PAD src0_sel:WORD_1 src1_sel:DWORD
	v_add3_u32 v46, v6, v46, s0
	v_add3_u32 v20, v7, v20, s0
	v_lshrrev_b32_e32 v46, 16, v46
	v_and_or_b32 v20, v20, s77, v46
	global_store_dword v[30:31], v20, off
	s_nop 1
	s_waitcnt vmcnt(7)
	v_lshlrev_b32_e32 v30, 16, v22
	v_and_b32_e32 v31, 0xffff0000, v22
	v_pk_fma_f32 v[6:7], v[4:5], v[6:7], v[30:31]
	v_lshl_add_u64 v[32:33], v[2:3], 0, s[40:41]
	v_and_b32_sdwa v22, v6, v9 dst_sel:DWORD dst_unused:UNUSED_PAD src0_sel:WORD_1 src1_sel:DWORD
	v_and_b32_sdwa v20, v7, v9 dst_sel:DWORD dst_unused:UNUSED_PAD src0_sel:WORD_1 src1_sel:DWORD
	v_add3_u32 v22, v6, v22, s0
	v_add3_u32 v20, v7, v20, s0
	v_lshrrev_b32_e32 v22, 16, v22
	v_and_or_b32 v20, v20, s77, v22
	s_waitcnt vmcnt(6)
	v_lshlrev_b32_e32 v22, 16, v23
	v_and_b32_e32 v23, 0xffff0000, v23
	v_pk_fma_f32 v[6:7], v[4:5], v[6:7], v[22:23]
	global_store_dword v[32:33], v20, off
	s_nop 1
	s_waitcnt vmcnt(5)
	v_and_b32_e32 v23, 0xffff0000, v24
	v_and_b32_sdwa v22, v6, v9 dst_sel:DWORD dst_unused:UNUSED_PAD src0_sel:WORD_1 src1_sel:DWORD
	v_and_b32_sdwa v20, v7, v9 dst_sel:DWORD dst_unused:UNUSED_PAD src0_sel:WORD_1 src1_sel:DWORD
	v_add3_u32 v22, v6, v22, s0
	v_add3_u32 v20, v7, v20, s0
	v_lshrrev_b32_e32 v22, 16, v22
	v_and_or_b32 v20, v20, s77, v22
	v_lshlrev_b32_e32 v22, 16, v24
	v_pk_fma_f32 v[6:7], v[4:5], v[6:7], v[22:23]
	v_lshl_add_u64 v[34:35], v[2:3], 0, s[42:43]
	v_and_b32_sdwa v22, v6, v9 dst_sel:DWORD dst_unused:UNUSED_PAD src0_sel:WORD_1 src1_sel:DWORD
	global_store_dword v[34:35], v20, off
	s_nop 1
	v_and_b32_sdwa v20, v7, v9 dst_sel:DWORD dst_unused:UNUSED_PAD src0_sel:WORD_1 src1_sel:DWORD
	v_add3_u32 v22, v6, v22, s0
	v_add3_u32 v20, v7, v20, s0
	v_lshrrev_b32_e32 v22, 16, v22
	v_and_or_b32 v20, v20, s77, v22
	s_waitcnt vmcnt(4)
	v_lshlrev_b32_e32 v22, 16, v25
	v_and_b32_e32 v23, 0xffff0000, v25
	v_pk_fma_f32 v[6:7], v[4:5], v[6:7], v[22:23]
	v_lshl_add_u64 v[36:37], v[2:3], 0, s[44:45]
	v_and_b32_sdwa v22, v6, v9 dst_sel:DWORD dst_unused:UNUSED_PAD src0_sel:WORD_1 src1_sel:DWORD
	global_store_dword v[36:37], v20, off
	s_nop 1
	v_and_b32_sdwa v20, v7, v9 dst_sel:DWORD dst_unused:UNUSED_PAD src0_sel:WORD_1 src1_sel:DWORD
	v_add3_u32 v22, v6, v22, s0
	v_add3_u32 v20, v7, v20, s0
	v_lshrrev_b32_e32 v22, 16, v22
	v_and_or_b32 v20, v20, s77, v22
	s_waitcnt vmcnt(3)
	v_lshlrev_b32_e32 v22, 16, v26
	v_and_b32_e32 v23, 0xffff0000, v26
	v_pk_fma_f32 v[6:7], v[4:5], v[6:7], v[22:23]
	v_lshl_add_u64 v[38:39], v[2:3], 0, s[46:47]
	v_and_b32_sdwa v22, v6, v9 dst_sel:DWORD dst_unused:UNUSED_PAD src0_sel:WORD_1 src1_sel:DWORD
	global_store_dword v[38:39], v20, off
	s_nop 1
	v_and_b32_sdwa v20, v7, v9 dst_sel:DWORD dst_unused:UNUSED_PAD src0_sel:WORD_1 src1_sel:DWORD
	v_add3_u32 v22, v6, v22, s0
	v_add3_u32 v20, v7, v20, s0
	v_lshrrev_b32_e32 v22, 16, v22
	v_and_or_b32 v20, v20, s77, v22
	s_waitcnt vmcnt(2)
	v_lshlrev_b32_e32 v22, 16, v27
	v_and_b32_e32 v23, 0xffff0000, v27
	v_pk_fma_f32 v[6:7], v[4:5], v[6:7], v[22:23]
	v_lshl_add_u64 v[40:41], v[2:3], 0, s[48:49]
	v_and_b32_sdwa v22, v6, v9 dst_sel:DWORD dst_unused:UNUSED_PAD src0_sel:WORD_1 src1_sel:DWORD
	global_store_dword v[40:41], v20, off
	s_nop 1
	v_and_b32_sdwa v20, v7, v9 dst_sel:DWORD dst_unused:UNUSED_PAD src0_sel:WORD_1 src1_sel:DWORD
	v_add3_u32 v22, v6, v22, s0
	v_add3_u32 v20, v7, v20, s0
	v_lshrrev_b32_e32 v22, 16, v22
	v_and_or_b32 v20, v20, s77, v22
	s_waitcnt vmcnt(1)
	v_lshlrev_b32_e32 v22, 16, v28
	v_and_b32_e32 v23, 0xffff0000, v28
	v_pk_fma_f32 v[6:7], v[4:5], v[6:7], v[22:23]
	v_lshl_add_u64 v[42:43], v[2:3], 0, s[50:51]
	v_and_b32_sdwa v22, v6, v9 dst_sel:DWORD dst_unused:UNUSED_PAD src0_sel:WORD_1 src1_sel:DWORD
	global_store_dword v[42:43], v20, off
	s_nop 1
	v_and_b32_sdwa v20, v7, v9 dst_sel:DWORD dst_unused:UNUSED_PAD src0_sel:WORD_1 src1_sel:DWORD
	v_add3_u32 v22, v6, v22, s0
	v_add3_u32 v20, v7, v20, s0
	v_lshrrev_b32_e32 v22, 16, v22
	v_lshl_add_u64 v[44:45], v[2:3], 0, s[52:53]
	v_and_or_b32 v20, v20, s77, v22
	global_store_dword v[44:45], v20, off
	s_nop 1
	s_waitcnt vmcnt(0)
	v_lshlrev_b32_e32 v22, 16, v29
	v_and_b32_e32 v23, 0xffff0000, v29
	s_add_i32 s85, s85, 16
	v_pk_fma_f32 v[6:7], v[4:5], v[6:7], v[22:23]
	v_lshl_add_u64 v[2:3], v[2:3], 0, s[56:57]
	s_and_b64 vcc, exec, s[82:83]
	v_mov_b32_e32 v20, v21
	s_cbranch_vccnz .LBB0_574
.LBB0_583:
	v_add_co_u32_e32 v22, vcc, 0x100000, v2
	v_lshl_add_u64 v[30:31], v[2:3], 0, s[4:5]
	s_nop 0
	v_addc_co_u32_e32 v23, vcc, 0, v3, vcc
	v_add_co_u32_e32 v24, vcc, 0x120000, v2
	global_load_dword v22, v[22:23], off
	s_nop 0
	v_addc_co_u32_e32 v25, vcc, 0, v3, vcc
	global_load_dword v23, v[24:25], off
	v_add_co_u32_e32 v24, vcc, 0x140000, v2
	v_lshl_add_u64 v[32:33], v[2:3], 0, s[58:59]
	s_nop 0
	v_addc_co_u32_e32 v25, vcc, 0, v3, vcc
	v_add_co_u32_e32 v26, vcc, 0x160000, v2
	global_load_dword v24, v[24:25], off
	s_nop 0
	v_addc_co_u32_e32 v27, vcc, 0, v3, vcc
	global_load_dword v25, v[26:27], off
	v_add_co_u32_e32 v26, vcc, 0x180000, v2
	v_lshl_add_u64 v[34:35], v[2:3], 0, s[60:61]
	s_nop 0
	v_addc_co_u32_e32 v27, vcc, 0, v3, vcc
	v_add_co_u32_e32 v28, vcc, 0x1a0000, v2
	global_load_dword v26, v[26:27], off
	s_nop 0
	v_addc_co_u32_e32 v29, vcc, 0, v3, vcc
	global_load_dword v27, v[28:29], off
	v_add_co_u32_e32 v28, vcc, 0x1c0000, v2
	v_lshl_add_u64 v[36:37], v[2:3], 0, s[62:63]
	s_nop 0
	v_addc_co_u32_e32 v29, vcc, 0, v3, vcc
	v_add_co_u32_e32 v44, vcc, 0x1e0000, v2
	global_load_dword v28, v[28:29], off
	s_nop 0
	v_addc_co_u32_e32 v45, vcc, 0, v3, vcc
	global_load_dword v29, v[44:45], off
	v_bfe_u32 v44, v6, 16, 1
	v_add3_u32 v44, v6, v44, s0
	v_bfe_u32 v45, v7, 16, 1
	v_lshrrev_b32_e32 v44, 16, v44
	v_add3_u32 v45, v7, v45, s0
	v_and_or_b32 v44, v45, s77, v44
	global_store_dword v[2:3], v44, off
	s_nop 1
	v_lshlrev_b32_e32 v44, 16, v1
	v_and_b32_e32 v45, 0xffff0000, v1
	v_pk_fma_f32 v[6:7], v[4:5], v[6:7], v[44:45]
	v_lshl_add_u64 v[38:39], v[2:3], 0, s[64:65]
	v_and_b32_sdwa v45, v6, v9 dst_sel:DWORD dst_unused:UNUSED_PAD src0_sel:WORD_1 src1_sel:DWORD
	v_and_b32_sdwa v44, v7, v9 dst_sel:DWORD dst_unused:UNUSED_PAD src0_sel:WORD_1 src1_sel:DWORD
	v_add3_u32 v45, v6, v45, s0
	v_add3_u32 v44, v7, v44, s0
	v_lshrrev_b32_e32 v45, 16, v45
	v_and_or_b32 v44, v44, s77, v45
	global_store_dword v[30:31], v44, off
	s_nop 1
	v_lshlrev_b32_e32 v30, 16, v8
	v_and_b32_e32 v31, 0xffff0000, v8
	v_pk_fma_f32 v[6:7], v[4:5], v[6:7], v[30:31]
	v_lshl_add_u64 v[40:41], v[2:3], 0, s[66:67]
	v_and_b32_sdwa v31, v6, v9 dst_sel:DWORD dst_unused:UNUSED_PAD src0_sel:WORD_1 src1_sel:DWORD
	v_and_b32_sdwa v30, v7, v9 dst_sel:DWORD dst_unused:UNUSED_PAD src0_sel:WORD_1 src1_sel:DWORD
	v_add3_u32 v31, v6, v31, s0
	v_add3_u32 v30, v7, v30, s0
	v_lshrrev_b32_e32 v31, 16, v31
	v_and_or_b32 v30, v30, s77, v31
	global_store_dword v[32:33], v30, off
	s_nop 1
	v_lshlrev_b32_e32 v30, 16, v10
	v_and_b32_e32 v31, 0xffff0000, v10
	v_pk_fma_f32 v[6:7], v[4:5], v[6:7], v[30:31]
	v_lshl_add_u64 v[42:43], v[2:3], 0, s[68:69]
	v_and_b32_sdwa v31, v6, v9 dst_sel:DWORD dst_unused:UNUSED_PAD src0_sel:WORD_1 src1_sel:DWORD
	v_and_b32_sdwa v30, v7, v9 dst_sel:DWORD dst_unused:UNUSED_PAD src0_sel:WORD_1 src1_sel:DWORD
	v_add3_u32 v31, v6, v31, s0
	v_add3_u32 v30, v7, v30, s0
	v_lshrrev_b32_e32 v31, 16, v31
	v_and_or_b32 v30, v30, s77, v31
	global_store_dword v[34:35], v30, off
	s_nop 1
	v_lshlrev_b32_e32 v30, 16, v12
	v_and_b32_e32 v31, 0xffff0000, v12
	v_pk_fma_f32 v[6:7], v[4:5], v[6:7], v[30:31]
	s_cmpk_gt_u32 s85, 0xef
	v_and_b32_sdwa v31, v6, v9 dst_sel:DWORD dst_unused:UNUSED_PAD src0_sel:WORD_1 src1_sel:DWORD
	v_and_b32_sdwa v30, v7, v9 dst_sel:DWORD dst_unused:UNUSED_PAD src0_sel:WORD_1 src1_sel:DWORD
	v_add3_u32 v31, v6, v31, s0
	v_add3_u32 v30, v7, v30, s0
	v_lshrrev_b32_e32 v31, 16, v31
	v_and_or_b32 v30, v30, s77, v31
	global_store_dword v[36:37], v30, off
	s_nop 1
	v_lshlrev_b32_e32 v30, 16, v14
	v_and_b32_e32 v31, 0xffff0000, v14
	v_pk_fma_f32 v[6:7], v[4:5], v[6:7], v[30:31]
	s_cselect_b64 s[82:83], -1, 0
	v_bfe_u32 v30, v6, 16, 1
	v_add3_u32 v30, v6, v30, s0
	v_bfe_u32 v31, v7, 16, 1
	v_lshrrev_b32_e32 v30, 16, v30
	v_add3_u32 v31, v7, v31, s0
	v_and_or_b32 v30, v31, s77, v30
	global_store_dword v[38:39], v30, off
	s_nop 1
	v_lshlrev_b32_e32 v30, 16, v16
	v_and_b32_e32 v31, 0xffff0000, v16
	v_pk_fma_f32 v[6:7], v[4:5], v[6:7], v[30:31]
	s_and_b64 vcc, exec, s[82:83]
	v_bfe_u32 v30, v6, 16, 1
	v_add3_u32 v30, v6, v30, s0
	v_bfe_u32 v31, v7, 16, 1
	v_lshrrev_b32_e32 v30, 16, v30
	v_add3_u32 v31, v7, v31, s0
	v_and_or_b32 v30, v31, s77, v30
	global_store_dword v[40:41], v30, off
	s_nop 1
	v_lshlrev_b32_e32 v30, 16, v18
	v_and_b32_e32 v31, 0xffff0000, v18
	v_pk_fma_f32 v[6:7], v[4:5], v[6:7], v[30:31]
	s_nop 0
	v_bfe_u32 v30, v6, 16, 1
	v_add3_u32 v30, v6, v30, s0
	v_bfe_u32 v31, v7, 16, 1
	v_lshrrev_b32_e32 v30, 16, v30
	v_add3_u32 v31, v7, v31, s0
	v_and_or_b32 v30, v31, s77, v30
	global_store_dword v[42:43], v30, off
	s_nop 1
	s_cbranch_vccnz .LBB0_582
	v_add_co_u32_e32 v30, vcc, 0x200000, v2
	s_nop 1
	v_addc_co_u32_e32 v31, vcc, 0, v3, vcc
	global_load_dword v1, v[30:31], off
	v_add_co_u32_e32 v30, vcc, 0x220000, v2
	s_nop 1
	v_addc_co_u32_e32 v31, vcc, 0, v3, vcc
	global_load_dword v8, v[30:31], off
	v_add_co_u32_e32 v30, vcc, 0x240000, v2
	s_nop 1
	v_addc_co_u32_e32 v31, vcc, 0, v3, vcc
	global_load_dword v10, v[30:31], off
	v_add_co_u32_e32 v30, vcc, 0x260000, v2
	s_nop 1
	v_addc_co_u32_e32 v31, vcc, 0, v3, vcc
	global_load_dword v12, v[30:31], off
	v_add_co_u32_e32 v30, vcc, 0x280000, v2
	s_nop 1
	v_addc_co_u32_e32 v31, vcc, 0, v3, vcc
	global_load_dword v14, v[30:31], off
	v_add_co_u32_e32 v30, vcc, 0x2a0000, v2
	s_nop 1
	v_addc_co_u32_e32 v31, vcc, 0, v3, vcc
	global_load_dword v16, v[30:31], off
	v_add_co_u32_e32 v30, vcc, 0x2c0000, v2
	s_nop 1
	v_addc_co_u32_e32 v31, vcc, 0, v3, vcc
	global_load_dword v18, v[30:31], off
	v_add_co_u32_e32 v30, vcc, 0x2e0000, v2
	s_nop 1
	v_addc_co_u32_e32 v31, vcc, 0, v3, vcc
	global_load_dword v21, v[30:31], off
	s_branch .LBB0_582
